# E2 mixers: dynamic priority inside loops (RG-LRU waves prio 2 only in gate/elementwise interval, GLA waves prio 2 in the other three intervals); on top of v50
# baseline (speedup 1.0000x reference)
; __device__ __forceinline__ float bf2f(bf16_t v) { return __uint_as_float(((unsigned)v) << 16); }
; __device__ __forceinline__ void rglru_unit(const Params& p, const WS& ws, int j, int u, bool dry = false) {
;     ...
;   auto body = [&](int tile, u32x4 (&xin)[4], bf16_t (&gav)[8]) {
;     const int t0 = 64 * tile;
; #pragma unroll
;     for (int i = 0; i < 4; ++i) {
;       const int ci = tid + 256 * i; const int row = ci >> 4, ch = ci & 15;
;       *(u32x4*)(XC + row * 136 + 8 * ch) = xin[i];
;     }
;     float gcur[8];
; #pragma unroll
;     for (int i = 0; i < 8; ++i) gcur[i] = bf2f(gav[i]);
;     __syncthreads();
;     flush_y();
;     if (tile + 2 < 33) prefetch(tile + 2, xin, gav);
.LBB0_1376:
	s_cmp_lt_i32 s4, 0
	ds_write_b128 v106, v[20:23]
	ds_write_b128 v107, v[24:27]
	ds_write_b128 v109, v[28:31]
	ds_write_b128 v110, v[32:35]
	s_waitcnt lgkmcnt(0)
	s_barrier
	s_setprio 2
	s_cbranch_scc1 .LBB0_1394
	v_add_u32_e32 v13, s4, v83
	v_cmp_gt_i32_e64 s[52:53], s15, v13
	s_and_saveexec_b64 s[4:5], s[52:53]
	s_cbranch_execz .LBB0_1385
	v_add_u32_e32 v52, v13, v84
	v_ashrrev_i32_e32 v53, 31, v52
	v_lshlrev_b64 v[52:53], 11, v[52:53]
	v_lshl_add_u64 v[52:53], v[74:75], 0, v[52:53]
	global_store_short v[52:53], v58, off
	s_or_b64 exec, exec, s[4:5]
	v_cmp_gt_i32_e64 s[52:53], s16, v13
	s_and_saveexec_b64 s[4:5], s[52:53]
	s_cbranch_execnz .LBB0_1386

; __device__ __forceinline__ float bf2f(bf16_t v) { return __uint_as_float(((unsigned)v) << 16); }
; __device__ __forceinline__ float sigmoidf_(float x) { return __builtin_amdgcn_rcpf(1.f + __expf(-x)); }
; #define MFMA16(a, b, c) __builtin_amdgcn_mfma_f32_16x16x32_bf16((a), (b), (c), 0, 0, 0)
; __device__ __forceinline__ void rglru_unit(const Params& p, const WS& ws, int j, int u, bool dry = false) {
;     ...
; #pragma unroll
;       for (int ks = 0; ks < 4; ++ks) {
;         const bf16x8 xf = *(const bf16x8*)(XC + (16 * w + lr) * 136 + 32 * ks + 8 * lq);
; #pragma unroll
;         for (int gate = 0; gate < 2; ++gate)
; #pragma unroll
;           for (int mt = 0; mt < 2; ++mt) {
;             const bf16x8 wf = *(const bf16x8*)(WG + (gate * 32 + 16 * mt + lr) * 136 + 32 * ks + 8 * lq);
;             ga_[gate][mt] = MFMA16(wf, xf, ga_[gate][mt]);
;           }
;       }
;       const int tok = 16 * w + lr;
; #pragma unroll
;       for (int mt = 0; mt < 2; ++mt)
; #pragma unroll
;         for (int jj = 0; jj < 4; ++jj) {
;           const int n = 16 * mt + 4 * lq + jj;
;           const float xcv = bf2f(XC[tok * 136 + 32 * jq + n]);
;           const float r = sigmoidf_(ga_[0][mt][jj] + ba[mt][jj]);
;           const float ig = sigmoidf_(ga_[1][mt][jj] + bx[mt][jj]);
;           const float la = -r * sp[mt][jj];
;           const float a = __expf(la);
;           const float x2 = 2.f * la;
;           const float om = x2 > -0.02f ? -x2 * (1.f + 0.5f * x2 * (1.f + x2 * (1.f / 3.f))) : 1.f - a * a;
;           const float mult = __builtin_amdgcn_sqrtf(fmaxf(om, 0.f));
;           AUa[tok * 33 + n] = a;
;           AUu[tok * 33 + n] = mult * ig * xcv;
;         }
.LBB0_1420:
	ds_read_b128 v[52:55], v111
	ds_read_b128 v[56:59], v112 offset:17408
	ds_read_b128 v[60:63], v112 offset:21760
	ds_read_b128 v[64:67], v112 offset:26112
	ds_read_b128 v[136:139], v112 offset:30464
	s_waitcnt lgkmcnt(3)
	v_mfma_f32_16x16x32_bf16 v[56:59], v[56:59], v[52:55], 0
	s_waitcnt lgkmcnt(2)
	v_mfma_f32_16x16x32_bf16 v[60:63], v[60:63], v[52:55], 0
	s_waitcnt lgkmcnt(1)
	v_mfma_f32_16x16x32_bf16 v[64:67], v[64:67], v[52:55], 0
	s_waitcnt lgkmcnt(0)
	v_mfma_f32_16x16x32_bf16 v[52:55], v[136:139], v[52:55], 0
	ds_read_b128 v[136:139], v111 offset:64
	ds_read_b128 v[140:143], v112 offset:17472
	s_waitcnt lgkmcnt(0)
	v_mfma_f32_16x16x32_bf16 v[56:59], v[140:143], v[136:139], v[56:59]
	ds_read_b128 v[140:143], v112 offset:21824
	s_waitcnt lgkmcnt(0)
	v_mfma_f32_16x16x32_bf16 v[60:63], v[140:143], v[136:139], v[60:63]
	ds_read_b128 v[140:143], v112 offset:26176
	s_waitcnt lgkmcnt(0)
	v_mfma_f32_16x16x32_bf16 v[64:67], v[140:143], v[136:139], v[64:67]
	ds_read_b128 v[140:143], v112 offset:30528
	s_waitcnt lgkmcnt(0)
	v_mfma_f32_16x16x32_bf16 v[52:55], v[140:143], v[136:139], v[52:55]
	ds_read_b128 v[136:139], v111 offset:128
	ds_read_b128 v[140:143], v112 offset:17536
	s_waitcnt lgkmcnt(0)
	v_mfma_f32_16x16x32_bf16 v[56:59], v[140:143], v[136:139], v[56:59]
	ds_read_b128 v[140:143], v112 offset:21888
	s_waitcnt lgkmcnt(0)
	v_mfma_f32_16x16x32_bf16 v[60:63], v[140:143], v[136:139], v[60:63]
	ds_read_b128 v[140:143], v112 offset:26240
	s_waitcnt lgkmcnt(0)
	v_mfma_f32_16x16x32_bf16 v[140:143], v[140:143], v[136:139], v[64:67]
	s_nop 2
	ds_read_b128 v[64:67], v112 offset:30592
	s_waitcnt lgkmcnt(0)
	v_mfma_f32_16x16x32_bf16 v[52:55], v[64:67], v[136:139], v[52:55]
	ds_read_b128 v[136:139], v111 offset:192
	ds_read_b128 v[64:67], v112 offset:17600
	ds_read_u16 v13, v113
	s_waitcnt lgkmcnt(1)
	v_mfma_f32_16x16x32_bf16 v[64:67], v[64:67], v[136:139], v[56:59]
	s_nop 2
	ds_read_b128 v[56:59], v112 offset:21952
	s_waitcnt lgkmcnt(0)
	v_mfma_f32_16x16x32_bf16 v[56:59], v[56:59], v[136:139], v[60:63]
	s_nop 2
	ds_read_b128 v[60:63], v112 offset:26304
	v_add_f32_e32 v14, v0, v64
	v_mul_f32_e32 v14, 0xbfb8aa3b, v14
	v_exp_f32_e32 v14, v14
	s_waitcnt lgkmcnt(0)
	v_mfma_f32_16x16x32_bf16 v[60:63], v[60:63], v[136:139], v[140:143]
	s_nop 2
	ds_read_b128 v[140:143], v112 offset:30656
	v_add_f32_e32 v14, 1.0, v14
	v_rcp_f32_e64 v14, -v14
	s_waitcnt lgkmcnt(0)
	v_mfma_f32_16x16x32_bf16 v[52:55], v[140:143], v[136:139], v[52:55]
	v_mul_f32_e32 v14, v89, v14
	v_mul_f32_e32 v15, 0x3fb8aa3b, v14
	v_exp_f32_e32 v15, v15
	v_add_f32_e32 v14, v14, v14
	v_cmp_nlt_f32_e64 s[52:53], s29, v14
	s_and_saveexec_b64 s[4:5], s[52:53]
	s_xor_b64 s[4:5], exec, s[4:5]
	v_fma_f32 v64, -v15, v15, 1.0
	s_andn2_saveexec_b64 s[4:5], s[4:5]
	v_pk_mul_f32 v[136:137], v[14:15], s[88:89] op_sel_hi:[0,1]
	v_add_f32_e32 v64, 1.0, v137
	v_fma_f32 v64, v136, v64, 1.0
	v_mul_f32_e64 v64, v64, -v14
	s_or_b64 exec, exec, s[4:5]
	v_add_f32_e32 v14, v8, v60
	v_max_f32_e32 v60, v64, v64
	v_add_f32_e32 v64, v1, v65
	v_mul_f32_e32 v14, 0xbfb8aa3b, v14
	v_mul_f32_e32 v64, 0xbfb8aa3b, v64
	v_exp_f32_e32 v14, v14
	v_exp_f32_e32 v64, v64
	v_max_f32_e32 v60, 0, v60
	v_sqrt_f32_e32 v60, v60
	v_add_f32_e32 v14, 1.0, v14
	v_add_f32_e32 v64, 1.0, v64
	v_rcp_f32_e32 v14, v14
	v_rcp_f32_e64 v64, -v64
	v_lshlrev_b32_e32 v13, 16, v13
	v_mul_f32_e32 v14, v14, v60
	v_mul_f32_e32 v64, v93, v64
	v_mul_f32_e32 v14, v14, v13
	ds_read_u16 v60, v113 offset:2
	v_mul_f32_e32 v13, 0x3fb8aa3b, v64
	v_exp_f32_e32 v13, v13
	ds_write2st64_b32 v72, v15, v14 offset0:136 offset1:169
	v_add_f32_e32 v14, v64, v64
	v_cmp_nlt_f32_e64 s[52:53], s29, v14
	s_and_saveexec_b64 s[4:5], s[52:53]
	s_xor_b64 s[4:5], exec, s[4:5]
	v_fma_f32 v15, -v13, v13, 1.0
	s_andn2_saveexec_b64 s[4:5], s[4:5]
	v_pk_mul_f32 v[64:65], v[14:15], s[88:89] op_sel_hi:[0,1]
	v_add_f32_e32 v15, 1.0, v65
	v_fma_f32 v15, v64, v15, 1.0
	v_mul_f32_e64 v15, v15, -v14
	s_or_b64 exec, exec, s[4:5]
	s_waitcnt lgkmcnt(1)
	v_lshlrev_b32_e32 v14, 16, v60
	v_add_f32_e32 v60, v9, v61
	v_mul_f32_e32 v60, 0xbfb8aa3b, v60
	v_exp_f32_e32 v60, v60
	v_max_f32_e32 v15, v15, v15
	v_max_f32_e32 v15, 0, v15
	v_sqrt_f32_e32 v15, v15
	v_add_f32_e32 v60, 1.0, v60
	v_rcp_f32_e32 v60, v60
	v_add_u32_e32 v135, 4, v72
	v_mul_f32_e32 v15, v60, v15
	v_mul_f32_e32 v14, v15, v14
	ds_write2st64_b32 v135, v13, v14 offset0:136 offset1:169
	v_add_f32_e32 v14, v2, v66
	v_mul_f32_e32 v14, 0xbfb8aa3b, v14
	v_exp_f32_e32 v14, v14
	ds_read_u16 v13, v113 offset:4
	v_add_f32_e32 v14, 1.0, v14
	v_rcp_f32_e64 v14, -v14
	s_nop 0
	v_mul_f32_e32 v14, v95, v14
	v_mul_f32_e32 v15, 0x3fb8aa3b, v14
	v_exp_f32_e32 v15, v15
	v_add_f32_e32 v14, v14, v14
	v_cmp_nlt_f32_e64 s[52:53], s29, v14
	s_and_saveexec_b64 s[4:5], s[52:53]
	s_xor_b64 s[4:5], exec, s[4:5]
	v_fma_f32 v60, -v15, v15, 1.0
	s_andn2_saveexec_b64 s[4:5], s[4:5]
	v_pk_mul_f32 v[60:61], v[14:15], s[88:89] op_sel_hi:[0,1]
	v_add_f32_e32 v61, 1.0, v61
	v_fma_f32 v60, v60, v61, 1.0
	v_mul_f32_e64 v60, v60, -v14
	s_or_b64 exec, exec, s[4:5]
	v_add_f32_e32 v14, v10, v62
	v_mul_f32_e32 v14, 0xbfb8aa3b, v14
	v_exp_f32_e32 v14, v14
	v_max_f32_e32 v60, v60, v60
	v_max_f32_e32 v60, 0, v60
	v_sqrt_f32_e32 v60, v60
	v_add_f32_e32 v14, 1.0, v14
	v_rcp_f32_e32 v14, v14
	s_waitcnt lgkmcnt(0)
; __device__ __forceinline__ float bf2f(bf16_t v) { return __uint_as_float(((unsigned)v) << 16); }
; __device__ __forceinline__ float sigmoidf_(float x) { return __builtin_amdgcn_rcpf(1.f + __expf(-x)); }
; __device__ __forceinline__ void rglru_unit(const Params& p, const WS& ws, int j, int u, bool dry = false) {
;     ...
; #pragma unroll
;       for (int mt = 0; mt < 2; ++mt)
; #pragma unroll
;         for (int jj = 0; jj < 4; ++jj) {
;           const int n = 16 * mt + 4 * lq + jj;
;           const float xcv = bf2f(XC[tok * 136 + 32 * jq + n]);
;           const float r = sigmoidf_(ga_[0][mt][jj] + ba[mt][jj]);
;           const float ig = sigmoidf_(ga_[1][mt][jj] + bx[mt][jj]);
;           const float la = -r * sp[mt][jj];
;           const float a = __expf(la);
;           const float x2 = 2.f * la;
;           const float om = x2 > -0.02f ? -x2 * (1.f + 0.5f * x2 * (1.f + x2 * (1.f / 3.f))) : 1.f - a * a;
;           const float mult = __builtin_amdgcn_sqrtf(fmaxf(om, 0.f));
;           AUa[tok * 33 + n] = a;
;           AUu[tok * 33 + n] = mult * ig * xcv;
;         }
;     }
;     __syncthreads();
	v_lshlrev_b32_e32 v13, 16, v13
	v_add_u32_e32 v136, 8, v72
	v_mul_f32_e32 v14, v14, v60
	v_mul_f32_e32 v13, v14, v13
	v_add_f32_e32 v14, v3, v67
	v_mul_f32_e32 v14, 0xbfb8aa3b, v14
	v_exp_f32_e32 v14, v14
	ds_write2st64_b32 v136, v15, v13 offset0:136 offset1:169
	ds_read_u16 v13, v113 offset:6
	v_add_f32_e32 v14, 1.0, v14
	v_rcp_f32_e64 v14, -v14
	s_nop 0
	v_mul_f32_e32 v14, v96, v14
	v_mul_f32_e32 v15, 0x3fb8aa3b, v14
	v_exp_f32_e32 v15, v15
	v_add_f32_e32 v14, v14, v14
	v_cmp_nlt_f32_e64 s[52:53], s29, v14
	s_and_saveexec_b64 s[4:5], s[52:53]
	s_xor_b64 s[4:5], exec, s[4:5]
	v_fma_f32 v60, -v15, v15, 1.0
	s_andn2_saveexec_b64 s[4:5], s[4:5]
	v_pk_mul_f32 v[60:61], v[14:15], s[88:89] op_sel_hi:[0,1]
	v_add_f32_e32 v61, 1.0, v61
	v_fma_f32 v60, v60, v61, 1.0
	v_mul_f32_e64 v60, v60, -v14
	s_or_b64 exec, exec, s[4:5]
	v_add_f32_e32 v14, v11, v63
	v_mul_f32_e32 v14, 0xbfb8aa3b, v14
	v_exp_f32_e32 v14, v14
	v_max_f32_e32 v60, v60, v60
	v_max_f32_e32 v60, 0, v60
	v_sqrt_f32_e32 v60, v60
	v_add_f32_e32 v14, 1.0, v14
	v_rcp_f32_e32 v14, v14
	s_waitcnt lgkmcnt(0)
	v_lshlrev_b32_e32 v13, 16, v13
	v_add_u32_e32 v139, 12, v72
	v_mul_f32_e32 v14, v14, v60
	v_mul_f32_e32 v13, v14, v13
	v_add_f32_e32 v14, v4, v56
	v_mul_f32_e32 v14, 0xbfb8aa3b, v14
	v_exp_f32_e32 v14, v14
	ds_write2st64_b32 v139, v15, v13 offset0:136 offset1:169
	ds_read_u16 v13, v113 offset:32
	v_add_f32_e32 v14, 1.0, v14
	v_rcp_f32_e64 v14, -v14
	s_nop 0
	v_mul_f32_e32 v14, v97, v14
	v_mul_f32_e32 v15, 0x3fb8aa3b, v14
	v_exp_f32_e32 v15, v15
	v_add_f32_e32 v14, v14, v14
	v_cmp_nlt_f32_e64 s[52:53], s29, v14
	s_and_saveexec_b64 s[4:5], s[52:53]
	s_xor_b64 s[4:5], exec, s[4:5]
	v_fma_f32 v56, -v15, v15, 1.0
	s_andn2_saveexec_b64 s[4:5], s[4:5]
	v_pk_mul_f32 v[60:61], v[14:15], s[88:89] op_sel_hi:[0,1]
	v_add_f32_e32 v56, 1.0, v61
	v_fma_f32 v56, v60, v56, 1.0
	v_mul_f32_e64 v56, v56, -v14
	s_or_b64 exec, exec, s[4:5]
	v_add_f32_e32 v14, v16, v52
	v_mul_f32_e32 v14, 0xbfb8aa3b, v14
	v_exp_f32_e32 v14, v14
	v_max_f32_e32 v52, v56, v56
	v_max_f32_e32 v52, 0, v52
	v_sqrt_f32_e32 v52, v52
	v_add_f32_e32 v14, 1.0, v14
	v_rcp_f32_e32 v14, v14
	s_waitcnt lgkmcnt(0)
	v_lshlrev_b32_e32 v13, 16, v13
	v_add_u32_e32 v141, 64, v72
	v_mul_f32_e32 v14, v14, v52
	v_mul_f32_e32 v13, v14, v13
	v_add_f32_e32 v14, v5, v57
	v_mul_f32_e32 v14, 0xbfb8aa3b, v14
	v_exp_f32_e32 v14, v14
	ds_write2st64_b32 v141, v15, v13 offset0:136 offset1:169
	ds_read_u16 v13, v113 offset:34
	v_add_f32_e32 v14, 1.0, v14
	v_rcp_f32_e64 v14, -v14
	s_nop 0
	v_mul_f32_e32 v14, v98, v14
	v_mul_f32_e32 v15, 0x3fb8aa3b, v14
	v_exp_f32_e32 v15, v15
	v_add_f32_e32 v14, v14, v14
	v_cmp_nlt_f32_e64 s[52:53], s29, v14
	s_and_saveexec_b64 s[4:5], s[52:53]
	s_xor_b64 s[4:5], exec, s[4:5]
	v_fma_f32 v52, -v15, v15, 1.0
	s_andn2_saveexec_b64 s[4:5], s[4:5]
	v_pk_mul_f32 v[56:57], v[14:15], s[88:89] op_sel_hi:[0,1]
	v_add_f32_e32 v52, 1.0, v57
	v_fma_f32 v52, v56, v52, 1.0
	v_mul_f32_e64 v52, v52, -v14
	s_or_b64 exec, exec, s[4:5]
	v_add_f32_e32 v14, v17, v53
	v_mul_f32_e32 v14, 0xbfb8aa3b, v14
	v_exp_f32_e32 v14, v14
	v_max_f32_e32 v52, v52, v52
	v_max_f32_e32 v52, 0, v52
	v_sqrt_f32_e32 v52, v52
	v_add_f32_e32 v14, 1.0, v14
	v_rcp_f32_e32 v14, v14
	s_waitcnt lgkmcnt(0)
	v_lshlrev_b32_e32 v13, 16, v13
	v_add_u32_e32 v142, 0x44, v72
	v_mul_f32_e32 v14, v14, v52
	v_mul_f32_e32 v13, v14, v13
	v_add_f32_e32 v14, v6, v58
	v_mul_f32_e32 v14, 0xbfb8aa3b, v14
	v_exp_f32_e32 v14, v14
	ds_write2st64_b32 v142, v15, v13 offset0:136 offset1:169
	ds_read_u16 v13, v113 offset:36
	v_add_f32_e32 v14, 1.0, v14
	v_rcp_f32_e64 v14, -v14
	s_nop 0
	v_mul_f32_e32 v14, v99, v14
	v_mul_f32_e32 v15, 0x3fb8aa3b, v14
	v_exp_f32_e32 v15, v15
	v_add_f32_e32 v14, v14, v14
	v_cmp_nlt_f32_e64 s[52:53], s29, v14
	s_and_saveexec_b64 s[4:5], s[52:53]
	s_xor_b64 s[4:5], exec, s[4:5]
	v_fma_f32 v52, -v15, v15, 1.0
	s_andn2_saveexec_b64 s[4:5], s[4:5]
	v_pk_mul_f32 v[52:53], v[14:15], s[88:89] op_sel_hi:[0,1]
	v_add_f32_e32 v53, 1.0, v53
	v_fma_f32 v52, v52, v53, 1.0
	v_mul_f32_e64 v52, v52, -v14
	s_or_b64 exec, exec, s[4:5]
	v_add_f32_e32 v14, v18, v54
	v_mul_f32_e32 v14, 0xbfb8aa3b, v14
	v_exp_f32_e32 v14, v14
	v_max_f32_e32 v52, v52, v52
	v_max_f32_e32 v52, 0, v52
	v_sqrt_f32_e32 v52, v52
	v_add_f32_e32 v14, 1.0, v14
	v_rcp_f32_e32 v14, v14
	s_waitcnt lgkmcnt(0)
	v_lshlrev_b32_e32 v13, 16, v13
	v_add_u32_e32 v144, 0x48, v72
	v_mul_f32_e32 v14, v14, v52
	v_mul_f32_e32 v13, v14, v13
	v_add_f32_e32 v14, v7, v59
	v_mul_f32_e32 v14, 0xbfb8aa3b, v14
	v_exp_f32_e32 v14, v14
	ds_write2st64_b32 v144, v15, v13 offset0:136 offset1:169
	ds_read_u16 v13, v113 offset:38
	v_add_f32_e32 v14, 1.0, v14
	v_rcp_f32_e64 v14, -v14
	s_nop 0
	v_mul_f32_e32 v14, v105, v14
	v_mul_f32_e32 v15, 0x3fb8aa3b, v14
	v_exp_f32_e32 v15, v15
	v_add_f32_e32 v14, v14, v14
	v_cmp_nlt_f32_e64 s[52:53], s29, v14
	s_and_saveexec_b64 s[4:5], s[52:53]
	s_xor_b64 s[4:5], exec, s[4:5]
	v_fma_f32 v52, -v15, v15, 1.0
	s_andn2_saveexec_b64 s[4:5], s[4:5]
	v_pk_mul_f32 v[52:53], v[14:15], s[88:89] op_sel_hi:[0,1]
	v_add_f32_e32 v53, 1.0, v53
	v_fma_f32 v52, v52, v53, 1.0
	v_mul_f32_e64 v52, v52, -v14
	s_or_b64 exec, exec, s[4:5]
	v_add_f32_e32 v14, v19, v55
	v_mul_f32_e32 v14, 0xbfb8aa3b, v14
	v_exp_f32_e32 v14, v14
	v_max_f32_e32 v52, v52, v52
	v_max_f32_e32 v52, 0, v52
	v_sqrt_f32_e32 v52, v52
	v_add_f32_e32 v14, 1.0, v14
	v_rcp_f32_e32 v14, v14
	s_waitcnt lgkmcnt(0)
	v_lshlrev_b32_e32 v13, 16, v13
	v_add_u32_e32 v145, 0x4c, v72
	v_add_u32_e32 v137, 0x8800, v114
	v_mul_f32_e32 v14, v14, v52
	v_mul_f32_e32 v13, v14, v13
	v_add_u32_e32 v138, 0xa800, v114
	ds_write2st64_b32 v145, v15, v13 offset0:136 offset1:169
	s_waitcnt lgkmcnt(0)
	s_barrier
; __device__ __forceinline__ void rglru_unit(const Params& p, const WS& ws, int j, int u, bool dry = false) {
;     ...
;     __syncthreads();
;     {
;       float A = 1.f, Hh = 0.f;
; #pragma unroll
;       for (int i = 0; i < 8; ++i) {
;         const float a = AUa[(8 * ssg + i) * 33 + sc], uu = AUu[(8 * ssg + i) * 33 + sc];
;         Hh = a * Hh + uu; A *= a;
;       }
;       SEGA[ssg * 32 + sc] = A; SEGH[ssg * 32 + sc] = Hh;
;     }
;     __syncthreads();
;     float hin = CARRY[sc];
; #pragma unroll
;     for (int s2 = 0; s2 < 7; ++s2)
;       if (s2 < ssg) hin = SEGA[s2 * 32 + sc] * hin + SEGH[s2 * 32 + sc];
	s_setprio 0
	ds_read2_b32 v[14:15], v137 offset1:33
	ds_read2_b32 v[52:53], v138 offset0:64 offset1:97
	v_add_u32_e32 v140, 0xac00, v114
	s_waitcnt lgkmcnt(0)
	v_fma_f32 v13, 0, v14, v52
	v_fmac_f32_e32 v53, v13, v15
	v_mul_f32_e32 v13, v14, v15
	ds_read2_b32 v[14:15], v137 offset0:66 offset1:99
	ds_read2_b32 v[54:55], v138 offset0:130 offset1:163
	s_waitcnt lgkmcnt(1)
	v_mul_f32_e32 v13, v13, v14
	s_waitcnt lgkmcnt(0)
	v_fma_f32 v52, v53, v14, v54
	v_fmac_f32_e32 v55, v52, v15
	v_mul_f32_e32 v13, v13, v15
	ds_read2_b32 v[14:15], v137 offset0:132 offset1:165
	ds_read2_b32 v[52:53], v138 offset0:196 offset1:229
	s_waitcnt lgkmcnt(1)
	v_mul_f32_e32 v13, v13, v14
	s_waitcnt lgkmcnt(0)
	v_fma_f32 v52, v55, v14, v52
	v_fmac_f32_e32 v53, v52, v15
	v_mul_f32_e32 v13, v13, v15
	ds_read2_b32 v[14:15], v137 offset0:198 offset1:231
	ds_read2_b32 v[54:55], v140 offset0:6 offset1:39
	s_waitcnt lgkmcnt(1)
	v_mul_f32_e32 v13, v13, v14
	s_waitcnt lgkmcnt(0)
	v_fma_f32 v52, v53, v14, v54
	v_fmac_f32_e32 v55, v52, v15
	v_mul_f32_e32 v13, v13, v15
	ds_write2st64_b32 v78, v13, v55 offset0:202 offset1:206
	s_waitcnt lgkmcnt(0)
	s_barrier
	ds_read_b32 v13, v115 offset:53760
	s_and_saveexec_b64 s[4:5], vcc
	s_cbranch_execz .LBB0_1548
	ds_read2st64_b32 v[14:15], v115 offset0:202 offset1:206
	s_waitcnt lgkmcnt(0)
	v_fmac_f32_e32 v15, v13, v14
	v_mov_b32_e32 v13, v15
	s_or_b64 exec, exec, s[4:5]
	v_add_u32_e32 v143, 0x80, v115
	s_and_saveexec_b64 s[4:5], s[38:39]
	s_cbranch_execnz .LBB0_1549

; __device__ __forceinline__ float bf2f(bf16_t v) { return __uint_as_float(((unsigned)v) << 16); }
; __device__ __forceinline__ bf16_t f2bf(float f) { return (bf16_t)(cvt_pk_bf16(f, 0.f) & 0xffffu); }
; __device__ __forceinline__ float siluf_(float x) { return x * __builtin_amdgcn_rcpf(1.f + __expf(-x)); }
; __device__ __forceinline__ void rglru_unit(const Params& p, const WS& ws, int j, int u, bool dry = false) {
;     ...
;   auto body = [&](int tile, u32x4 (&xin)[4], bf16_t (&gav)[8]) {
;     const int t0 = 64 * tile;
; #pragma unroll
;     for (int i = 0; i < 4; ++i) {
;       const int ci = tid + 256 * i; const int row = ci >> 4, ch = ci & 15;
;       *(u32x4*)(XC + row * 136 + 8 * ch) = xin[i];
;     }
;     float gcur[8];
; #pragma unroll
;     for (int i = 0; i < 8; ++i) gcur[i] = bf2f(gav[i]);
;     __syncthreads();
;     flush_y();
;     ...
;     __syncthreads();
;     {
;       float h = hin;
; #pragma unroll
;       for (int i = 0; i < 8; ++i) {
;         const float a = AUa[(8 * ssg + i) * 33 + sc], uu = AUu[(8 * ssg + i) * 33 + sc];
;         h = a * h + uu;
;         const int t = t0 + 8 * ssg + i;
;         ypend[i] = f2bf(h * siluf_(gcur[i]));
;       }
;       if (ssg == 7) CARRY[sc] = h;
;       ypend_t0 = t0;
.LBB0_1460:
	s_or_b64 exec, exec, s[4:5]
	s_waitcnt lgkmcnt(0)
	s_barrier
	ds_read2_b32 v[14:15], v137 offset1:33
	ds_read2_b32 v[56:57], v138 offset0:64 offset1:97
	s_waitcnt lgkmcnt(0)
	v_fma_f32 v56, v13, v14, v56
	v_fmac_f32_e32 v57, v56, v15
	ds_read2_b32 v[14:15], v137 offset0:66 offset1:99
	ds_read2_b32 v[54:55], v138 offset0:130 offset1:163
	s_waitcnt lgkmcnt(0)
	v_fma_f32 v54, v57, v14, v54
	v_fmac_f32_e32 v55, v54, v15
	ds_read2_b32 v[14:15], v137 offset0:132 offset1:165
	ds_read2_b32 v[52:53], v138 offset0:196 offset1:229
	s_waitcnt lgkmcnt(0)
	v_fma_f32 v52, v55, v14, v52
	v_fmac_f32_e32 v53, v52, v15
	ds_read2_b32 v[58:59], v137 offset0:198 offset1:231
	ds_read2_b32 v[14:15], v140 offset0:6 offset1:39
	s_waitcnt lgkmcnt(0)
	v_fma_f32 v13, v53, v58, v14
	v_fmac_f32_e32 v15, v13, v59
	s_and_saveexec_b64 s[4:5], s[50:51]
	ds_write_b32 v115, v15 offset:53760
	s_or_b64 exec, exec, s[4:5]
	v_lshlrev_b32_e32 v14, 16, v120
	v_mul_f32_e32 v58, 0xbfb8aa3b, v14
	v_exp_f32_e32 v58, v58
	v_lshlrev_b32_e32 v59, 16, v119
	v_lshlrev_b32_e32 v60, 16, v122
	v_lshlrev_b32_e32 v61, 16, v121
	v_add_f32_e32 v58, 1.0, v58
	v_rcp_f32_e32 v58, v58
	v_lshlrev_b32_e32 v62, 16, v124
	v_lshlrev_b32_e32 v63, 16, v123
	v_lshlrev_b32_e32 v64, 16, v128
	v_mul_f32_e32 v14, v58, v14
	v_mul_f32_e32 v14, v14, v56
	v_cvt_pk_bf16_f32 v58, v14, s0
	v_mul_f32_e32 v14, 0xbfb8aa3b, v59
	v_exp_f32_e32 v14, v14
	v_lshlrev_b32_e32 v65, 16, v127
	s_cmp_gt_u32 s7, 32
	v_add_f32_e32 v14, 1.0, v14
	v_rcp_f32_e32 v14, v14
	s_nop 0
	v_mul_f32_e32 v14, v14, v59
	v_mul_f32_e32 v14, v14, v57
	v_cvt_pk_bf16_f32 v59, v14, s0
	v_mul_f32_e32 v14, 0xbfb8aa3b, v60
	v_exp_f32_e32 v14, v14
	s_nop 0
	v_add_f32_e32 v14, 1.0, v14
	v_rcp_f32_e32 v14, v14
	s_nop 0
	v_mul_f32_e32 v14, v14, v60
	v_mul_f32_e32 v14, v14, v54
	v_cvt_pk_bf16_f32 v56, v14, s0
	v_mul_f32_e32 v14, 0xbfb8aa3b, v61
	v_exp_f32_e32 v14, v14
	s_nop 0
	v_add_f32_e32 v14, 1.0, v14
	v_rcp_f32_e32 v14, v14
	s_nop 0
	v_mul_f32_e32 v14, v14, v61
	v_mul_f32_e32 v14, v14, v55
	v_cvt_pk_bf16_f32 v57, v14, s0
	v_mul_f32_e32 v14, 0xbfb8aa3b, v62
	v_exp_f32_e32 v14, v14
	s_nop 0
	v_add_f32_e32 v14, 1.0, v14
	v_rcp_f32_e32 v14, v14
	s_nop 0
	v_mul_f32_e32 v14, v14, v62
	v_mul_f32_e32 v14, v14, v52
	v_cvt_pk_bf16_f32 v54, v14, s0
	v_mul_f32_e32 v14, 0xbfb8aa3b, v63
	v_exp_f32_e32 v14, v14
	s_nop 0
	v_add_f32_e32 v14, 1.0, v14
	v_rcp_f32_e32 v14, v14
	s_nop 0
	v_mul_f32_e32 v14, v14, v63
	v_mul_f32_e32 v14, v14, v53
	v_cvt_pk_bf16_f32 v55, v14, s0
	v_mul_f32_e32 v14, 0xbfb8aa3b, v64
	v_exp_f32_e32 v14, v14
	s_nop 0
	v_add_f32_e32 v14, 1.0, v14
	v_rcp_f32_e32 v14, v14
	s_nop 0
	v_mul_f32_e32 v14, v14, v64
	v_mul_f32_e32 v13, v14, v13
	v_cvt_pk_bf16_f32 v14, v13, s0
	v_mul_f32_e32 v13, 0xbfb8aa3b, v65
	v_exp_f32_e32 v13, v13
	s_nop 0
	v_add_f32_e32 v13, 1.0, v13
	v_rcp_f32_e32 v13, v13
	s_nop 0
	v_mul_f32_e32 v13, v13, v65
	v_mul_f32_e32 v13, v13, v15
	v_cvt_pk_bf16_f32 v15, v13, s0
	s_cbranch_scc1 .LBB0_1554
	v_add_u32_e32 v60, s6, v83
	v_cmp_gt_i32_e64 s[52:53], s15, v60
	v_add_u32_e32 v52, s6, v69
	ds_write_b128 v106, v[36:39]
	ds_write_b128 v107, v[40:43]
	ds_write_b128 v109, v[44:47]
	ds_write_b128 v110, v[48:51]
	s_waitcnt lgkmcnt(0)
	s_barrier
	s_setprio 2
	s_and_saveexec_b64 s[4:5], s[52:53]
	s_cbranch_execz .LBB0_1465
	v_ashrrev_i32_e32 v53, 31, v52
	v_lshlrev_b64 v[62:63], 11, v[52:53]
	v_lshl_add_u64 v[62:63], v[74:75], 0, v[62:63]
	global_store_short v[62:63], v58, off

; __device__ __forceinline__ float bf2f(bf16_t v) { return __uint_as_float(((unsigned)v) << 16); }
; __device__ __forceinline__ float sigmoidf_(float x) { return __builtin_amdgcn_rcpf(1.f + __expf(-x)); }
; #define MFMA16(a, b, c) __builtin_amdgcn_mfma_f32_16x16x32_bf16((a), (b), (c), 0, 0, 0)
; __device__ __forceinline__ void rglru_unit(const Params& p, const WS& ws, int j, int u, bool dry = false) {
;     ...
; #pragma unroll
;       for (int ks = 0; ks < 4; ++ks) {
;         const bf16x8 xf = *(const bf16x8*)(XC + (16 * w + lr) * 136 + 32 * ks + 8 * lq);
; #pragma unroll
;         for (int gate = 0; gate < 2; ++gate)
; #pragma unroll
;           for (int mt = 0; mt < 2; ++mt) {
;             const bf16x8 wf = *(const bf16x8*)(WG + (gate * 32 + 16 * mt + lr) * 136 + 32 * ks + 8 * lq);
;             ga_[gate][mt] = MFMA16(wf, xf, ga_[gate][mt]);
;           }
;       }
;       const int tok = 16 * w + lr;
; #pragma unroll
;       for (int mt = 0; mt < 2; ++mt)
; #pragma unroll
;         for (int jj = 0; jj < 4; ++jj) {
;           const int n = 16 * mt + 4 * lq + jj;
;           const float xcv = bf2f(XC[tok * 136 + 32 * jq + n]);
;           const float r = sigmoidf_(ga_[0][mt][jj] + ba[mt][jj]);
;           const float ig = sigmoidf_(ga_[1][mt][jj] + bx[mt][jj]);
;           const float la = -r * sp[mt][jj];
;           const float a = __expf(la);
;           const float x2 = 2.f * la;
;           const float om = x2 > -0.02f ? -x2 * (1.f + 0.5f * x2 * (1.f + x2 * (1.f / 3.f))) : 1.f - a * a;
;           const float mult = __builtin_amdgcn_sqrtf(fmaxf(om, 0.f));
;           AUa[tok * 33 + n] = a;
;           AUu[tok * 33 + n] = mult * ig * xcv;
;         }
.LBB0_1505:
	ds_read_b128 v[52:55], v111
	ds_read_b128 v[56:59], v112 offset:17408
	ds_read_b128 v[60:63], v112 offset:21760
	ds_read_b128 v[64:67], v112 offset:26112
	ds_read_b128 v[120:123], v112 offset:30464
	s_waitcnt lgkmcnt(3)
	v_mfma_f32_16x16x32_bf16 v[56:59], v[56:59], v[52:55], 0
	s_waitcnt lgkmcnt(2)
	v_mfma_f32_16x16x32_bf16 v[60:63], v[60:63], v[52:55], 0
	s_waitcnt lgkmcnt(1)
	v_mfma_f32_16x16x32_bf16 v[64:67], v[64:67], v[52:55], 0
	s_waitcnt lgkmcnt(0)
	v_mfma_f32_16x16x32_bf16 v[52:55], v[120:123], v[52:55], 0
	ds_read_b128 v[120:123], v111 offset:64
	ds_read_b128 v[154:157], v112 offset:17472
	s_waitcnt lgkmcnt(0)
	v_mfma_f32_16x16x32_bf16 v[56:59], v[154:157], v[120:123], v[56:59]
	ds_read_b128 v[154:157], v112 offset:21824
	s_waitcnt lgkmcnt(0)
	v_mfma_f32_16x16x32_bf16 v[60:63], v[154:157], v[120:123], v[60:63]
	ds_read_b128 v[154:157], v112 offset:26176
	s_waitcnt lgkmcnt(0)
	v_mfma_f32_16x16x32_bf16 v[64:67], v[154:157], v[120:123], v[64:67]
	ds_read_b128 v[154:157], v112 offset:30528
	s_waitcnt lgkmcnt(0)
	v_mfma_f32_16x16x32_bf16 v[52:55], v[154:157], v[120:123], v[52:55]
	ds_read_b128 v[120:123], v111 offset:128
	ds_read_b128 v[154:157], v112 offset:17536
	s_waitcnt lgkmcnt(0)
	v_mfma_f32_16x16x32_bf16 v[56:59], v[154:157], v[120:123], v[56:59]
	ds_read_b128 v[154:157], v112 offset:21888
	s_waitcnt lgkmcnt(0)
	v_mfma_f32_16x16x32_bf16 v[60:63], v[154:157], v[120:123], v[60:63]
	ds_read_b128 v[154:157], v112 offset:26240
	s_waitcnt lgkmcnt(0)
	v_mfma_f32_16x16x32_bf16 v[154:157], v[154:157], v[120:123], v[64:67]
	s_nop 2
	ds_read_b128 v[64:67], v112 offset:30592
	s_waitcnt lgkmcnt(0)
	v_mfma_f32_16x16x32_bf16 v[52:55], v[64:67], v[120:123], v[52:55]
	ds_read_b128 v[120:123], v111 offset:192
	ds_read_b128 v[64:67], v112 offset:17600
	ds_read_u16 v15, v113
	s_waitcnt lgkmcnt(1)
	v_mfma_f32_16x16x32_bf16 v[64:67], v[64:67], v[120:123], v[56:59]
	s_nop 2
	ds_read_b128 v[56:59], v112 offset:21952
	s_waitcnt lgkmcnt(0)
	v_mfma_f32_16x16x32_bf16 v[56:59], v[56:59], v[120:123], v[60:63]
	s_nop 2
	ds_read_b128 v[60:63], v112 offset:26304
	v_add_f32_e32 v14, v0, v64
	v_mul_f32_e32 v14, 0xbfb8aa3b, v14
	v_exp_f32_e32 v14, v14
	s_waitcnt lgkmcnt(0)
	v_mfma_f32_16x16x32_bf16 v[60:63], v[60:63], v[120:123], v[154:157]
	s_nop 2
	ds_read_b128 v[154:157], v112 offset:30656
	v_add_f32_e32 v14, 1.0, v14
	v_rcp_f32_e64 v14, -v14
	s_waitcnt lgkmcnt(0)
	v_mfma_f32_16x16x32_bf16 v[52:55], v[154:157], v[120:123], v[52:55]
	v_mul_f32_e32 v14, v89, v14
	v_mul_f32_e32 v64, 0x3fb8aa3b, v14
	v_exp_f32_e32 v64, v64
	v_add_f32_e32 v14, v14, v14
	v_cmp_nlt_f32_e64 s[52:53], s29, v14
	s_and_saveexec_b64 s[4:5], s[52:53]
	s_xor_b64 s[4:5], exec, s[4:5]
	v_fma_f32 v119, -v64, v64, 1.0
	s_andn2_saveexec_b64 s[4:5], s[4:5]
	v_pk_mul_f32 v[120:121], v[14:15], s[88:89] op_sel_hi:[0,1]
	v_add_f32_e32 v119, 1.0, v121
	v_fma_f32 v119, v120, v119, 1.0
	v_mul_f32_e64 v119, v119, -v14
	s_or_b64 exec, exec, s[4:5]
	v_add_f32_e32 v14, v8, v60
	v_add_f32_e32 v65, v1, v65
	v_mul_f32_e32 v14, 0xbfb8aa3b, v14
	v_mul_f32_e32 v65, 0xbfb8aa3b, v65
	v_exp_f32_e32 v14, v14
	v_exp_f32_e32 v65, v65
	v_max_f32_e32 v60, v119, v119
	v_max_f32_e32 v60, 0, v60
	v_add_f32_e32 v14, 1.0, v14
	v_add_f32_e32 v65, 1.0, v65
	v_rcp_f32_e32 v14, v14
	v_sqrt_f32_e32 v60, v60
	v_rcp_f32_e64 v65, -v65
	v_lshlrev_b32_e32 v15, 16, v15
	v_mul_f32_e32 v14, v14, v60
	v_mul_f32_e32 v65, v93, v65
	v_mul_f32_e32 v14, v14, v15
	ds_read_u16 v60, v113 offset:2
	v_mul_f32_e32 v15, 0x3fb8aa3b, v65
	v_exp_f32_e32 v15, v15
	ds_write2st64_b32 v72, v64, v14 offset0:136 offset1:169
	v_add_f32_e32 v14, v65, v65
	v_cmp_nlt_f32_e64 s[52:53], s29, v14
	s_and_saveexec_b64 s[4:5], s[52:53]
	s_xor_b64 s[4:5], exec, s[4:5]
	v_fma_f32 v64, -v15, v15, 1.0
	s_andn2_saveexec_b64 s[4:5], s[4:5]
	v_pk_mul_f32 v[64:65], v[14:15], s[88:89] op_sel_hi:[0,1]
	v_add_f32_e32 v65, 1.0, v65
	v_fma_f32 v64, v64, v65, 1.0
	v_mul_f32_e64 v64, v64, -v14
	s_or_b64 exec, exec, s[4:5]
	v_add_f32_e32 v14, v9, v61
	v_max_f32_e32 v61, v64, v64
	v_add_f32_e32 v64, v2, v66
	v_mul_f32_e32 v14, 0xbfb8aa3b, v14
	v_mul_f32_e32 v64, 0xbfb8aa3b, v64
	v_exp_f32_e32 v14, v14
	v_exp_f32_e32 v64, v64
	v_max_f32_e32 v61, 0, v61
	v_sqrt_f32_e32 v61, v61
	v_add_f32_e32 v14, 1.0, v14
	v_add_f32_e32 v64, 1.0, v64
	v_rcp_f32_e32 v14, v14
	v_rcp_f32_e64 v64, -v64
	s_waitcnt lgkmcnt(1)
	v_lshlrev_b32_e32 v60, 16, v60
	v_mul_f32_e32 v14, v14, v61
	v_mul_f32_e32 v64, v95, v64
	v_mul_f32_e32 v14, v14, v60
	ds_read_u16 v61, v113 offset:4
	v_mul_f32_e32 v60, 0x3fb8aa3b, v64
	v_exp_f32_e32 v60, v60
	ds_write2st64_b32 v135, v15, v14 offset0:136 offset1:169
	v_add_f32_e32 v14, v64, v64
	v_cmp_nlt_f32_e64 s[52:53], s29, v14
	s_and_saveexec_b64 s[4:5], s[52:53]
	s_xor_b64 s[4:5], exec, s[4:5]
	v_fma_f32 v15, -v60, v60, 1.0
	s_andn2_saveexec_b64 s[4:5], s[4:5]
	v_pk_mul_f32 v[64:65], v[14:15], s[88:89] op_sel_hi:[0,1]
	v_add_f32_e32 v15, 1.0, v65
	v_fma_f32 v15, v64, v15, 1.0
	v_mul_f32_e64 v15, v15, -v14
	s_or_b64 exec, exec, s[4:5]
	v_add_f32_e32 v14, v10, v62
	v_add_f32_e32 v62, v3, v67
	v_mul_f32_e32 v14, 0xbfb8aa3b, v14
	v_mul_f32_e32 v62, 0xbfb8aa3b, v62
	v_exp_f32_e32 v14, v14
	v_exp_f32_e32 v62, v62
	v_max_f32_e32 v15, v15, v15
	v_max_f32_e32 v15, 0, v15
	v_add_f32_e32 v14, 1.0, v14
	v_add_f32_e32 v62, 1.0, v62
	v_rcp_f32_e32 v14, v14
	v_sqrt_f32_e32 v15, v15
	v_rcp_f32_e64 v62, -v62
	s_waitcnt lgkmcnt(1)
; __device__ __forceinline__ float bf2f(bf16_t v) { return __uint_as_float(((unsigned)v) << 16); }
; __device__ __forceinline__ float sigmoidf_(float x) { return __builtin_amdgcn_rcpf(1.f + __expf(-x)); }
; __device__ __forceinline__ void rglru_unit(const Params& p, const WS& ws, int j, int u, bool dry = false) {
;     ...
;       const int tok = 16 * w + lr;
; #pragma unroll
;       for (int mt = 0; mt < 2; ++mt)
; #pragma unroll
;         for (int jj = 0; jj < 4; ++jj) {
;           const int n = 16 * mt + 4 * lq + jj;
;           const float xcv = bf2f(XC[tok * 136 + 32 * jq + n]);
;           const float r = sigmoidf_(ga_[0][mt][jj] + ba[mt][jj]);
;           const float ig = sigmoidf_(ga_[1][mt][jj] + bx[mt][jj]);
;           const float la = -r * sp[mt][jj];
;           const float a = __expf(la);
;           const float x2 = 2.f * la;
;           const float om = x2 > -0.02f ? -x2 * (1.f + 0.5f * x2 * (1.f + x2 * (1.f / 3.f))) : 1.f - a * a;
;           const float mult = __builtin_amdgcn_sqrtf(fmaxf(om, 0.f));
;           AUa[tok * 33 + n] = a;
;           AUu[tok * 33 + n] = mult * ig * xcv;
;         }
;     }
;     __syncthreads();
;     {
;       float A = 1.f, Hh = 0.f;
; #pragma unroll
;       for (int i = 0; i < 8; ++i) {
;         const float a = AUa[(8 * ssg + i) * 33 + sc], uu = AUu[(8 * ssg + i) * 33 + sc];
;         Hh = a * Hh + uu; A *= a;
;       }
;       SEGA[ssg * 32 + sc] = A; SEGH[ssg * 32 + sc] = Hh;
;     }
;     __syncthreads();
;     float hin = CARRY[sc];
; #pragma unroll
;     for (int s2 = 0; s2 < 7; ++s2)
;       if (s2 < ssg) hin = SEGA[s2 * 32 + sc] * hin + SEGH[s2 * 32 + sc];
	v_lshlrev_b32_e32 v61, 16, v61
	v_mul_f32_e32 v14, v14, v15
	v_mul_f32_e32 v62, v96, v62
	v_mul_f32_e32 v14, v14, v61
	ds_read_u16 v61, v113 offset:6
	v_mul_f32_e32 v15, 0x3fb8aa3b, v62
	v_exp_f32_e32 v15, v15
	ds_write2st64_b32 v136, v60, v14 offset0:136 offset1:169
	v_add_f32_e32 v14, v62, v62
	v_cmp_nlt_f32_e64 s[52:53], s29, v14
	s_and_saveexec_b64 s[4:5], s[52:53]
	s_xor_b64 s[4:5], exec, s[4:5]
	v_fma_f32 v60, -v15, v15, 1.0
	s_andn2_saveexec_b64 s[4:5], s[4:5]
	v_pk_mul_f32 v[64:65], v[14:15], s[88:89] op_sel_hi:[0,1]
	v_add_f32_e32 v60, 1.0, v65
	v_fma_f32 v60, v64, v60, 1.0
	v_mul_f32_e64 v60, v60, -v14
	s_or_b64 exec, exec, s[4:5]
	v_add_f32_e32 v14, v11, v63
	v_mul_f32_e32 v14, 0xbfb8aa3b, v14
	v_add_f32_e32 v56, v4, v56
	v_exp_f32_e32 v14, v14
	v_mul_f32_e32 v56, 0xbfb8aa3b, v56
	v_exp_f32_e32 v56, v56
	v_max_f32_e32 v60, v60, v60
	v_add_f32_e32 v14, 1.0, v14
	v_max_f32_e32 v60, 0, v60
	v_rcp_f32_e32 v14, v14
	v_sqrt_f32_e32 v60, v60
	v_add_f32_e32 v56, 1.0, v56
	v_rcp_f32_e64 v56, -v56
	s_waitcnt lgkmcnt(1)
	v_lshlrev_b32_e32 v61, 16, v61
	v_mul_f32_e32 v14, v14, v60
	v_mul_f32_e32 v14, v14, v61
	v_mul_f32_e32 v61, v97, v56
	ds_read_u16 v60, v113 offset:32
	v_mul_f32_e32 v56, 0x3fb8aa3b, v61
	v_exp_f32_e32 v56, v56
	ds_write2st64_b32 v139, v15, v14 offset0:136 offset1:169
	v_add_f32_e32 v14, v61, v61
	v_cmp_nlt_f32_e64 s[52:53], s29, v14
	s_and_saveexec_b64 s[4:5], s[52:53]
	s_xor_b64 s[4:5], exec, s[4:5]
	v_fma_f32 v15, -v56, v56, 1.0
	s_andn2_saveexec_b64 s[4:5], s[4:5]
	v_pk_mul_f32 v[62:63], v[14:15], s[88:89] op_sel_hi:[0,1]
	v_add_f32_e32 v15, 1.0, v63
	v_fma_f32 v15, v62, v15, 1.0
	v_mul_f32_e64 v15, v15, -v14
	s_or_b64 exec, exec, s[4:5]
	v_add_f32_e32 v14, v16, v52
	v_mul_f32_e32 v14, 0xbfb8aa3b, v14
	v_add_f32_e32 v52, v5, v57
	v_exp_f32_e32 v14, v14
	v_mul_f32_e32 v52, 0xbfb8aa3b, v52
	v_exp_f32_e32 v52, v52
	v_max_f32_e32 v15, v15, v15
	v_add_f32_e32 v14, 1.0, v14
	v_max_f32_e32 v15, 0, v15
	v_rcp_f32_e32 v14, v14
	v_sqrt_f32_e32 v15, v15
	v_add_f32_e32 v52, 1.0, v52
	s_waitcnt lgkmcnt(1)
	v_lshlrev_b32_e32 v57, 16, v60
	v_rcp_f32_e64 v60, -v52
	v_mul_f32_e32 v14, v14, v15
	v_mul_f32_e32 v14, v14, v57
	ds_read_u16 v52, v113 offset:34
	v_mul_f32_e32 v57, v98, v60
	v_mul_f32_e32 v15, 0x3fb8aa3b, v57
	v_exp_f32_e32 v15, v15
	ds_write2st64_b32 v141, v56, v14 offset0:136 offset1:169
	v_add_f32_e32 v14, v57, v57
	v_cmp_nlt_f32_e64 s[52:53], s29, v14
	s_and_saveexec_b64 s[4:5], s[52:53]
	s_xor_b64 s[4:5], exec, s[4:5]
	v_fma_f32 v56, -v15, v15, 1.0
	s_andn2_saveexec_b64 s[4:5], s[4:5]
	v_pk_mul_f32 v[56:57], v[14:15], s[88:89] op_sel_hi:[0,1]
	v_add_f32_e32 v57, 1.0, v57
	v_fma_f32 v56, v56, v57, 1.0
	v_mul_f32_e64 v56, v56, -v14
	s_or_b64 exec, exec, s[4:5]
	v_add_f32_e32 v14, v17, v53
	v_max_f32_e32 v53, v56, v56
	v_add_f32_e32 v56, v6, v58
	v_mul_f32_e32 v14, 0xbfb8aa3b, v14
	v_mul_f32_e32 v56, 0xbfb8aa3b, v56
	v_exp_f32_e32 v14, v14
	v_exp_f32_e32 v56, v56
	v_max_f32_e32 v53, 0, v53
	v_sqrt_f32_e32 v53, v53
	v_add_f32_e32 v14, 1.0, v14
	v_add_f32_e32 v56, 1.0, v56
	v_rcp_f32_e32 v14, v14
	v_rcp_f32_e64 v56, -v56
	s_waitcnt lgkmcnt(1)
	v_lshlrev_b32_e32 v52, 16, v52
	v_mul_f32_e32 v14, v14, v53
	v_mul_f32_e32 v56, v99, v56
	v_mul_f32_e32 v14, v14, v52
	ds_read_u16 v53, v113 offset:36
	v_mul_f32_e32 v52, 0x3fb8aa3b, v56
	v_exp_f32_e32 v52, v52
	ds_write2st64_b32 v142, v15, v14 offset0:136 offset1:169
	v_add_f32_e32 v14, v56, v56
	v_cmp_nlt_f32_e64 s[52:53], s29, v14
	s_and_saveexec_b64 s[4:5], s[52:53]
	s_xor_b64 s[4:5], exec, s[4:5]
	v_fma_f32 v15, -v52, v52, 1.0
	s_andn2_saveexec_b64 s[4:5], s[4:5]
	v_pk_mul_f32 v[56:57], v[14:15], s[88:89] op_sel_hi:[0,1]
	v_add_f32_e32 v15, 1.0, v57
	v_fma_f32 v15, v56, v15, 1.0
	v_mul_f32_e64 v15, v15, -v14
	s_or_b64 exec, exec, s[4:5]
	v_add_f32_e32 v14, v18, v54
	v_add_f32_e32 v54, v7, v59
	v_mul_f32_e32 v14, 0xbfb8aa3b, v14
	v_mul_f32_e32 v54, 0xbfb8aa3b, v54
	v_exp_f32_e32 v14, v14
	v_exp_f32_e32 v54, v54
	v_max_f32_e32 v15, v15, v15
	v_max_f32_e32 v15, 0, v15
	v_add_f32_e32 v14, 1.0, v14
	v_add_f32_e32 v54, 1.0, v54
	v_rcp_f32_e32 v14, v14
	v_sqrt_f32_e32 v15, v15
	v_rcp_f32_e64 v54, -v54
	s_waitcnt lgkmcnt(1)
	v_lshlrev_b32_e32 v53, 16, v53
	v_mul_f32_e32 v14, v14, v15
	v_mul_f32_e32 v54, v105, v54
	v_mul_f32_e32 v14, v14, v53
	ds_read_u16 v53, v113 offset:38
	v_mul_f32_e32 v15, 0x3fb8aa3b, v54
	v_exp_f32_e32 v15, v15
	ds_write2st64_b32 v144, v52, v14 offset0:136 offset1:169
	v_add_f32_e32 v14, v54, v54
	v_cmp_nlt_f32_e64 s[52:53], s29, v14
	s_and_saveexec_b64 s[4:5], s[52:53]
	s_xor_b64 s[4:5], exec, s[4:5]
	v_fma_f32 v52, -v15, v15, 1.0
	s_andn2_saveexec_b64 s[4:5], s[4:5]
	v_pk_mul_f32 v[56:57], v[14:15], s[88:89] op_sel_hi:[0,1]
	v_add_f32_e32 v52, 1.0, v57
	v_fma_f32 v52, v56, v52, 1.0
	v_mul_f32_e64 v52, v52, -v14
	s_or_b64 exec, exec, s[4:5]
	s_waitcnt lgkmcnt(1)
	v_lshlrev_b32_e32 v14, 16, v53
	v_add_f32_e32 v53, v19, v55
	v_mul_f32_e32 v53, 0xbfb8aa3b, v53
	v_exp_f32_e32 v53, v53
	v_max_f32_e32 v52, v52, v52
	v_max_f32_e32 v52, 0, v52
	v_sqrt_f32_e32 v52, v52
	v_add_f32_e32 v53, 1.0, v53
	v_rcp_f32_e32 v53, v53
	s_nop 0
	v_mul_f32_e32 v52, v53, v52
	v_mul_f32_e32 v14, v52, v14
	ds_write2st64_b32 v145, v15, v14 offset0:136 offset1:169
	s_waitcnt lgkmcnt(0)
	s_barrier
	s_setprio 0
	ds_read2_b32 v[14:15], v137 offset1:33
	ds_read2_b32 v[52:53], v138 offset0:64 offset1:97
	s_waitcnt lgkmcnt(0)
	v_fma_f32 v52, 0, v14, v52
	v_fmac_f32_e32 v53, v52, v15
	v_mul_f32_e32 v52, v14, v15
	ds_read2_b32 v[14:15], v137 offset0:66 offset1:99
	ds_read2_b32 v[54:55], v138 offset0:130 offset1:163
	s_waitcnt lgkmcnt(0)
	v_fma_f32 v53, v53, v14, v54
	v_mul_f32_e32 v14, v52, v14
	v_fmac_f32_e32 v55, v53, v15
	v_mul_f32_e32 v54, v14, v15
	ds_read2_b32 v[14:15], v137 offset0:132 offset1:165
	ds_read2_b32 v[52:53], v138 offset0:196 offset1:229
	s_waitcnt lgkmcnt(0)
	v_fma_f32 v52, v55, v14, v52
	v_mul_f32_e32 v14, v54, v14
	v_fmac_f32_e32 v53, v52, v15
	v_mul_f32_e32 v52, v14, v15
	ds_read2_b32 v[14:15], v137 offset0:198 offset1:231
	ds_read2_b32 v[54:55], v140 offset0:6 offset1:39
	s_waitcnt lgkmcnt(0)
	v_fma_f32 v53, v53, v14, v54
	v_mul_f32_e32 v14, v52, v14
	v_fmac_f32_e32 v55, v53, v15
	v_mul_f32_e32 v14, v14, v15
	ds_write2st64_b32 v78, v14, v55 offset0:202 offset1:206
	s_waitcnt lgkmcnt(0)
	s_barrier
	ds_read_b32 v14, v115 offset:53760
	s_and_saveexec_b64 s[4:5], vcc
	s_cbranch_execz .LBB0_1557
	ds_read2st64_b32 v[52:53], v115 offset0:202 offset1:206
	s_waitcnt lgkmcnt(0)
	v_fmac_f32_e32 v53, v14, v52
	v_mov_b32_e32 v14, v53
	s_or_b64 exec, exec, s[4:5]
	s_and_saveexec_b64 s[4:5], s[38:39]
	s_cbranch_execnz .LBB0_1558

; __device__ __forceinline__ void gla_unit(const Params& p, const WS& ws, int u, bool dry = false) {
;     ...
;   auto flush_o = [&]() {
;     if (tpend >= 0 && !dry) {
;       const size_t row = (size_t)(b * T_ + tpend);
; #pragma unroll
;       for (int mt = 0; mt < 2; ++mt) *(u32x2*)(ws.V + row * 1024 + hd * 256 + sl * 32 + 16 * mt + 4 * lq) = opend[mt];
;       if (lq == 0) ws.SSQ[row * 32 + hd * 8 + sl] = sqpend;
;     }
;     ...
;   auto body = [&](int c, u32x4 (&qr)[4], u32x4 (&kr)[4], u32x4& vr, float (&ebl)[2]) {
; #pragma unroll
;     for (int i = 0; i < 4; ++i) {
;       const int ci = tid + 256 * i; const int row = ci >> 4, ch = ci & 15;
;       *(u32x4*)(QDs + row * 136 + ch * 8) = qr[i];
;       *(u32x4*)(KIs + row * 136 + ch * 8) = kr[i];
;       const unsigned kk[4] = {kr[i].x, kr[i].y, kr[i].z, kr[i].w};
; #pragma unroll
;       for (int e = 0; e < 4; ++e) {
;         KIT[(ch * 8 + 2 * e) * 72 + (row ^ ((ch & 7) << 3))] = (bf16_t)(kk[e] & 0xffffu);
;         KIT[(ch * 8 + 2 * e + 1) * 72 + (row ^ ((ch & 7) << 3))] = (bf16_t)(kk[e] >> 16);
;       }
;     }
;     {
;       const int row = tid >> 2, ch = tid & 3;
;       const unsigned vv[4] = {vr.x, vr.y, vr.z, vr.w};
; #pragma unroll
;       for (int e = 0; e < 4; ++e) {
;         VTs[(ch * 8 + 2 * e) * 72 + (row ^ (ch << 3))] = (bf16_t)(vv[e] & 0xffffu);
;         VTs[(ch * 8 + 2 * e + 1) * 72 + (row ^ (ch << 3))] = (bf16_t)(vv[e] >> 16);
;       }
;     }
;     const float eb0 = ebl[0], eb1 = ebl[1];
;     __syncthreads();
;     flush_o();
.LBB0_1607:
	v_cmp_lt_i32_e64 s[80:81], -1, v11
	ds_write_b128 v147, v[28:31]
	ds_write_b128 v147, v[16:19] offset:17408
	ds_write_b16 v148, v16 offset:34816
	ds_write_b16_d16_hi v149, v16 offset:34960
	ds_write_b16 v148, v17 offset:35104
	ds_write_b16_d16_hi v148, v17 offset:35248
	ds_write_b16 v148, v18 offset:35392
	ds_write_b16_d16_hi v148, v18 offset:35536
	ds_write_b16 v148, v19 offset:35680
	ds_write_b16_d16_hi v148, v19 offset:35824
	ds_write_b128 v150, v[32:35]
	ds_write_b128 v150, v[20:23] offset:17408
	ds_write_b16 v151, v20 offset:34816
	ds_write_b16_d16_hi v152, v20 offset:34960
	ds_write_b16 v151, v21 offset:35104
	ds_write_b16_d16_hi v151, v21 offset:35248
	ds_write_b16 v151, v22 offset:35392
	ds_write_b16_d16_hi v151, v22 offset:35536
	ds_write_b16 v151, v23 offset:35680
	ds_write_b16_d16_hi v151, v23 offset:35824
	ds_write_b128 v153, v[36:39]
	ds_write_b128 v153, v[24:27] offset:17408
	ds_write_b16 v154, v24 offset:34816
	ds_write_b16_d16_hi v155, v24 offset:34960
	ds_write_b16 v154, v25 offset:35104
	ds_write_b16_d16_hi v154, v25 offset:35248
	ds_write_b16 v154, v26 offset:35392
	ds_write_b16_d16_hi v154, v26 offset:35536
	ds_write_b16 v154, v27 offset:35680
	ds_write_b16_d16_hi v154, v27 offset:35824
	ds_write_b128 v156, v[40:43]
	s_waitcnt vmcnt(4)
	ds_write_b128 v156, v[60:63] offset:17408
	ds_write_b16 v157, v60 offset:34816
	ds_write_b16_d16_hi v158, v60 offset:34960
	ds_write_b16 v157, v61 offset:35104
	ds_write_b16_d16_hi v157, v61 offset:35248
	ds_write_b16 v157, v62 offset:35392
	ds_write_b16_d16_hi v157, v62 offset:35536
	ds_write_b16 v157, v63 offset:35680
	ds_write_b16_d16_hi v157, v63 offset:35824
	ds_write_b16 v159, v0 offset:53248
	ds_write_b16_d16_hi v160, v0 offset:53392
	ds_write_b16 v159, v1 offset:53536
	ds_write_b16_d16_hi v159, v1 offset:53680
	ds_write_b16 v159, v2 offset:53824
	ds_write_b16_d16_hi v159, v2 offset:53968
	ds_write_b16 v159, v3 offset:54112
	ds_write_b16_d16_hi v159, v3 offset:54256
	s_waitcnt lgkmcnt(0)
	s_barrier
	s_setprio 0
	s_and_saveexec_b64 s[12:13], s[80:81]
	s_cbranch_execz .LBB0_1610
	v_add_u32_e32 v8, v11, v146
	v_ashrrev_i32_e32 v9, 31, v8
	v_lshlrev_b64 v[14:15], 11, v[8:9]
	v_lshl_add_u64 v[14:15], v[138:139], 0, v[14:15]
	global_store_dwordx2 v[14:15], v[4:5], off
	global_store_dwordx2 v[14:15], v[6:7], off offset:32
	s_and_b64 exec, exec, s[44:45]
	s_cbranch_execz .LBB0_1610
	v_lshlrev_b64 v[4:5], 7, v[8:9]
	v_lshl_add_u64 v[4:5], s[6:7], 0, v[4:5]
	global_store_dword v[4:5], v10, off

; #define MFMA16(a, b, c) __builtin_amdgcn_mfma_f32_16x16x32_bf16((a), (b), (c), 0, 0, 0)
; __device__ __forceinline__ void gla_unit(const Params& p, const WS& ws, int u, bool dry = false) {
;     ...
;       *(u32x2*)(Ps + irow * 72 + 16 * mt + 4 * lq) = pk;
;     }
;     __syncthreads();
;     f32x4 oacc[2];
;     oacc[0] = (f32x4){0.f, 0.f, 0.f, 0.f}; oacc[1] = (f32x4){0.f, 0.f, 0.f, 0.f};
; #pragma unroll
;     for (int ks = 0; ks < 2; ++ks) {
;       if (2 * ks <= w) {
;         const bf16x8 pb = *(const bf16x8*)(Ps + irow * 72 + 32 * ks + 8 * lq);
; #pragma unroll
;         for (int mt = 0; mt < 2; ++mt) {
;           const bf16x8 vf = *(const bf16x8*)(VTs + (16 * mt + lr) * 72 + (((4 * ks + lq) ^ (((16 * mt + lr) >> 3) & 3)) << 3));
;           oacc[mt] = MFMA16(vf, pb, oacc[mt]);
;         }
;       }
;     }
.LBB0_1630:
	s_or_b64 exec, exec, s[12:13]
	v_mov_b32_e32 v112, 0
	v_mov_b32_e32 v113, 0
	v_mov_b32_e32 v114, 0
	v_mov_b32_e32 v115, 0
	v_mov_b32_e32 v108, 0
	v_mov_b32_e32 v109, 0
	v_mov_b32_e32 v110, 0
	v_mov_b32_e32 v111, 0
	v_mov_b32_e32 v116, 0
	v_mov_b32_e32 v117, 0
	v_mov_b32_e32 v118, 0
	v_mov_b32_e32 v119, 0
	v_mov_b32_e32 v120, 0
	v_mov_b32_e32 v121, 0
	v_mov_b32_e32 v122, 0
	v_mov_b32_e32 v123, 0
	ds_write_b64 v182, v[14:15] offset:96
	s_waitcnt lgkmcnt(0)
	s_barrier
	s_setprio 2
	s_and_saveexec_b64 s[12:13], vcc
	s_cbranch_execz .LBB0_1632
	ds_read_b128 v[108:111], v170 offset:53248
	ds_read_b128 v[116:119], v177
	ds_read_b128 v[120:123], v171 offset:53248
	s_waitcnt lgkmcnt(1)
	v_mfma_f32_16x16x32_bf16 v[112:115], v[108:111], v[116:119], 0
	s_waitcnt lgkmcnt(0)
	v_mfma_f32_16x16x32_bf16 v[108:111], v[120:123], v[116:119], 0
	s_nop 5
	v_mov_b32_e32 v116, v112
	v_mov_b32_e32 v117, v113
	v_mov_b32_e32 v118, v114
	v_mov_b32_e32 v119, v115
	v_mov_b32_e32 v120, v108
	v_mov_b32_e32 v121, v109
	v_mov_b32_e32 v122, v110
	v_mov_b32_e32 v123, v111

; __device__ __forceinline__ bf16_t f2bf(float f) { return (bf16_t)(cvt_pk_bf16(f, 0.f) & 0xffffu); }
; #define MFMA16(a, b, c) __builtin_amdgcn_mfma_f32_16x16x32_bf16((a), (b), (c), 0, 0, 0)
; __device__ __forceinline__ void gla_unit(const Params& p, const WS& ws, int u, bool dry = false) {
;     ...
; #pragma unroll
;     for (int ks = 0; ks < 4; ++ks)
; #pragma unroll
;       for (int mt = 0; mt < 2; ++mt) {
;         const bf16x8 sf = *(const bf16x8*)(STs + (16 * mt + lr) * 136 + 32 * ks + 8 * lq);
;         oacc[mt] = MFMA16(sf, xq[ks], oacc[mt]);
;       }
;     {
;       const int t = 64 * c - 48 + irow;
;       float sq = 0.f;
; #pragma unroll
;       for (int mt = 0; mt < 2; ++mt) sq += oacc[mt][0] * oacc[mt][0] + oacc[mt][1] * oacc[mt][1] + oacc[mt][2] * oacc[mt][2] + oacc[mt][3] * oacc[mt][3];
;       sq += __shfl_xor(sq, 16); sq += __shfl_xor(sq, 32);
;       tpend = t;
;       sqpend = sq;
; #pragma unroll
;       for (int mt = 0; mt < 2; ++mt) { opend[mt].x = cvt_pk_bf16(oacc[mt][0], oacc[mt][1]); opend[mt].y = cvt_pk_bf16(oacc[mt][2], oacc[mt][3]); }
;     }
;     __syncthreads();
; #pragma unroll
;     for (int ntl = 0; ntl < 2; ++ntl) {
; #pragma unroll
;       for (int ks = 0; ks < 2; ++ks) {
;         const bf16x8 kf = *(const bf16x8*)(KIT + (16 * (2 * w + ntl) + lr) * 72 + (((4 * ks + lq) ^ (((16 * (2 * w + ntl) + lr) >> 3) & 7)) << 3));
; #pragma unroll
;         for (int mt = 0; mt < 2; ++mt) {
;           const bf16x8 vf = *(const bf16x8*)(VTs + (16 * mt + lr) * 72 + (((4 * ks + lq) ^ (((16 * mt + lr) >> 3) & 3)) << 3));
;           sacc[mt][ntl] = MFMA16(vf, kf, sacc[mt][ntl]);
;         }
;       }
;       const float e = ntl ? eb1 : eb0;
; #pragma unroll
;       for (int mt = 0; mt < 2; ++mt) {
;         sacc[mt][ntl] = scale4(sacc[mt][ntl], e);
; #pragma unroll
;         for (int jj = 0; jj < 4; ++jj) STs[(16 * mt + 4 * lq + jj) * 136 + 16 * (2 * w + ntl) + lr] = f2bf(sacc[mt][ntl][jj]);
;       }
;     }
;     __syncthreads();
.LBB0_1634:
	s_or_b64 exec, exec, s[12:13]
	s_nop 1
	ds_read_b128 v[108:111], v129 offset:57856
	ds_read_b128 v[112:115], v129 offset:62208
	s_cmp_gt_u32 s35, 32
	s_waitcnt lgkmcnt(1)
	v_mfma_f32_16x16x32_bf16 v[108:111], v[108:111], v[104:107], v[116:119]
	s_waitcnt lgkmcnt(0)
	v_mfma_f32_16x16x32_bf16 v[104:107], v[112:115], v[104:107], v[120:123]
	ds_read_b128 v[112:115], v129 offset:57920
	s_waitcnt lgkmcnt(0)
	v_mfma_f32_16x16x32_bf16 v[108:111], v[112:115], v[100:103], v[108:111]
	ds_read_b128 v[112:115], v129 offset:62272
	s_waitcnt lgkmcnt(0)
	v_mfma_f32_16x16x32_bf16 v[100:103], v[112:115], v[100:103], v[104:107]
	s_nop 2
	ds_read_b128 v[104:107], v129 offset:57984
	s_waitcnt lgkmcnt(0)
	v_mfma_f32_16x16x32_bf16 v[104:107], v[104:107], v[8:11], v[108:111]
	s_nop 2
	ds_read_b128 v[108:111], v129 offset:62336
	s_waitcnt lgkmcnt(0)
	v_mfma_f32_16x16x32_bf16 v[8:11], v[108:111], v[8:11], v[100:103]
	s_nop 2
	ds_read_b128 v[100:103], v129 offset:58048
	s_waitcnt lgkmcnt(0)
	v_mfma_f32_16x16x32_bf16 v[100:103], v[100:103], v[4:7], v[104:107]
	s_nop 2
	ds_read_b128 v[104:107], v129 offset:62400
	s_waitcnt lgkmcnt(0)
	s_barrier
	v_mfma_f32_16x16x32_bf16 v[6:9], v[104:107], v[4:7], v[8:11]
	s_nop 2
	v_mov_b32_e32 v10, v101
	v_mov_b32_e32 v4, v100
	s_nop 2
	v_mov_b32_e32 v11, v7
	v_mov_b32_e32 v5, v6
	v_pk_mul_f32 v[10:11], v[10:11], v[10:11]
	v_cvt_pk_bf16_f32 v6, v6, v7
	v_pk_fma_f32 v[4:5], v[4:5], v[4:5], v[10:11]
	v_mov_b32_e32 v10, v102
	v_mov_b32_e32 v11, v8
	v_pk_fma_f32 v[4:5], v[10:11], v[10:11], v[4:5]
	v_mov_b32_e32 v10, v103
	v_mov_b32_e32 v11, v9
	v_pk_fma_f32 v[4:5], v[10:11], v[10:11], v[4:5]
	v_cvt_pk_bf16_f32 v7, v8, v9
	v_add_f32_e32 v4, v4, v5
	ds_bpermute_b32 v5, v163, v4
	v_mov_b32_e32 v8, v208
	s_waitcnt lgkmcnt(0)
	v_add_f32_e32 v4, v4, v5
	ds_bpermute_b32 v5, v168, v4
	s_waitcnt lgkmcnt(0)
	v_add_f32_e32 v10, v4, v5
	v_cvt_pk_bf16_f32 v4, v100, v101
	v_cvt_pk_bf16_f32 v5, v102, v103
	ds_read_b128 v[100:103], v169 offset:34816
	ds_read_b128 v[104:107], v170 offset:53248
	s_waitcnt lgkmcnt(0)
	v_mfma_f32_16x16x32_bf16 v[84:87], v[104:107], v[100:103], v[84:87]
	ds_read_b128 v[104:107], v171 offset:53248
	s_waitcnt lgkmcnt(0)
	v_mfma_f32_16x16x32_bf16 v[96:99], v[104:107], v[100:103], v[96:99]
	ds_read_b128 v[100:103], v172 offset:34816
	ds_read_b128 v[104:107], v173 offset:53248
	s_waitcnt lgkmcnt(0)
	v_mfma_f32_16x16x32_bf16 v[84:87], v[104:107], v[100:103], v[84:87]
	ds_read_b128 v[104:107], v174 offset:53248
	s_waitcnt lgkmcnt(0)
	v_mfma_f32_16x16x32_bf16 v[96:99], v[104:107], v[100:103], v[96:99]
	s_nop 4
	v_mul_f32_e32 v84, v84, v8
	v_mul_f32_e32 v85, v85, v8
	v_mul_f32_e32 v86, v86, v8
	v_mul_f32_e32 v87, v87, v8
	s_nop 0
	v_cvt_pk_bf16_f32 v8, v84, s0
	ds_write_b16 v178, v8 offset:57856
	v_cvt_pk_bf16_f32 v8, v85, s0
	ds_write_b16 v178, v8 offset:58128
	v_cvt_pk_bf16_f32 v8, v86, s0
	ds_write_b16 v178, v8 offset:58400
	v_cvt_pk_bf16_f32 v8, v87, s0
	ds_write_b16 v178, v8 offset:58672
	s_nop 0
	v_mul_f32_e32 v96, v96, v208
	v_mul_f32_e32 v97, v97, v208
	v_mul_f32_e32 v98, v98, v208
	v_mul_f32_e32 v99, v99, v208
	s_nop 0
	v_cvt_pk_bf16_f32 v8, v96, s0
	ds_write_b16 v178, v8 offset:62208
	v_cvt_pk_bf16_f32 v8, v97, s0
	ds_write_b16 v178, v8 offset:62480
	v_cvt_pk_bf16_f32 v8, v98, s0
	ds_write_b16 v178, v8 offset:62752
	v_cvt_pk_bf16_f32 v8, v99, s0
	ds_write_b16 v178, v8 offset:63024
	ds_read_b128 v[100:103], v180 offset:34816
	ds_read_b128 v[104:107], v170 offset:53248
	s_waitcnt lgkmcnt(0)
	v_mfma_f32_16x16x32_bf16 v[88:91], v[104:107], v[100:103], v[88:91]
	ds_read_b128 v[104:107], v171 offset:53248
	v_mov_b32_e32 v8, v207
	s_waitcnt lgkmcnt(0)
	v_mfma_f32_16x16x32_bf16 v[92:95], v[104:107], v[100:103], v[92:95]
	ds_read_b128 v[100:103], v181 offset:34816
	ds_read_b128 v[104:107], v173 offset:53248
	s_waitcnt lgkmcnt(0)
	v_mfma_f32_16x16x32_bf16 v[88:91], v[104:107], v[100:103], v[88:91]
	ds_read_b128 v[104:107], v174 offset:53248
	s_waitcnt lgkmcnt(0)
	v_mfma_f32_16x16x32_bf16 v[92:95], v[104:107], v[100:103], v[92:95]
	s_nop 4
	v_mul_f32_e32 v88, v88, v8
	v_mul_f32_e32 v89, v89, v8
	v_mul_f32_e32 v90, v90, v8
	v_mul_f32_e32 v91, v91, v8
	s_nop 0
	v_cvt_pk_bf16_f32 v8, v88, s0
	ds_write_b16 v178, v8 offset:57888
	v_cvt_pk_bf16_f32 v8, v89, s0
	ds_write_b16 v178, v8 offset:58160
	v_cvt_pk_bf16_f32 v8, v90, s0
	ds_write_b16 v178, v8 offset:58432
	v_cvt_pk_bf16_f32 v8, v91, s0
	ds_write_b16 v178, v8 offset:58704
	s_nop 0
	v_mul_f32_e32 v92, v92, v207
	v_mul_f32_e32 v93, v93, v207
	v_mul_f32_e32 v94, v94, v207
	v_mul_f32_e32 v95, v95, v207
	s_nop 0
	v_cvt_pk_bf16_f32 v8, v92, s0
	ds_write_b16 v178, v8 offset:62240
	v_cvt_pk_bf16_f32 v8, v93, s0
	ds_write_b16 v178, v8 offset:62512
	v_cvt_pk_bf16_f32 v8, v94, s0
	ds_write_b16 v178, v8 offset:62784
	v_cvt_pk_bf16_f32 v8, v95, s0
	ds_write_b16 v178, v8 offset:63056
	s_waitcnt lgkmcnt(0)
	s_barrier
; __device__ __forceinline__ void gla_unit(const Params& p, const WS& ws, int u, bool dry = false) {
;     ...
;   auto flush_o = [&]() {
;     if (tpend >= 0 && !dry) {
;       const size_t row = (size_t)(b * T_ + tpend);
; #pragma unroll
;       for (int mt = 0; mt < 2; ++mt) *(u32x2*)(ws.V + row * 1024 + hd * 256 + sl * 32 + 16 * mt + 4 * lq) = opend[mt];
;       if (lq == 0) ws.SSQ[row * 32 + hd * 8 + sl] = sqpend;
;     }
;     ...
;   auto body = [&](int c, u32x4 (&qr)[4], u32x4 (&kr)[4], u32x4& vr, float (&ebl)[2]) {
; #pragma unroll
;     for (int i = 0; i < 4; ++i) {
;       const int ci = tid + 256 * i; const int row = ci >> 4, ch = ci & 15;
;       *(u32x4*)(QDs + row * 136 + ch * 8) = qr[i];
;       *(u32x4*)(KIs + row * 136 + ch * 8) = kr[i];
;       const unsigned kk[4] = {kr[i].x, kr[i].y, kr[i].z, kr[i].w};
; #pragma unroll
;       for (int e = 0; e < 4; ++e) {
;         KIT[(ch * 8 + 2 * e) * 72 + (row ^ ((ch & 7) << 3))] = (bf16_t)(kk[e] & 0xffffu);
;         KIT[(ch * 8 + 2 * e + 1) * 72 + (row ^ ((ch & 7) << 3))] = (bf16_t)(kk[e] >> 16);
;       }
;     }
;     {
;       const int row = tid >> 2, ch = tid & 3;
;       const unsigned vv[4] = {vr.x, vr.y, vr.z, vr.w};
; #pragma unroll
;       for (int e = 0; e < 4; ++e) {
;         VTs[(ch * 8 + 2 * e) * 72 + (row ^ (ch << 3))] = (bf16_t)(vv[e] & 0xffffu);
;         VTs[(ch * 8 + 2 * e + 1) * 72 + (row ^ (ch << 3))] = (bf16_t)(vv[e] >> 16);
;       }
;     }
;     const float eb0 = ebl[0], eb1 = ebl[1];
;     __syncthreads();
;     flush_o();
	s_cbranch_scc1 .LBB0_1663
	v_add_u32_e32 v207, s92, v161
	v_subrev_u32_e32 v8, 48, v207
	v_cmp_lt_i32_e64 s[80:81], -1, v8
	ds_write_b128 v147, v[44:47]
	ds_write_b128 v147, v[48:51] offset:17408
	ds_write_b16 v148, v48 offset:34816
	ds_write_b16_d16_hi v149, v48 offset:34960
	ds_write_b16 v148, v49 offset:35104
	ds_write_b16_d16_hi v148, v49 offset:35248
	ds_write_b16 v148, v50 offset:35392
	ds_write_b16_d16_hi v148, v50 offset:35536
	ds_write_b16 v148, v51 offset:35680
	ds_write_b16_d16_hi v148, v51 offset:35824
	ds_write_b128 v150, v[56:59]
	ds_write_b128 v150, v[52:55] offset:17408
	ds_write_b16 v151, v52 offset:34816
	ds_write_b16_d16_hi v152, v52 offset:34960
	ds_write_b16 v151, v53 offset:35104
	ds_write_b16_d16_hi v151, v53 offset:35248
	ds_write_b16 v151, v54 offset:35392
	ds_write_b16_d16_hi v151, v54 offset:35536
	ds_write_b16 v151, v55 offset:35680
	ds_write_b16_d16_hi v151, v55 offset:35824
	ds_write_b128 v153, v[64:67]
	ds_write_b128 v153, v[68:71] offset:17408
	ds_write_b16 v154, v68 offset:34816
	ds_write_b16_d16_hi v155, v68 offset:34960
	ds_write_b16 v154, v69 offset:35104
	ds_write_b16_d16_hi v154, v69 offset:35248
	ds_write_b16 v154, v70 offset:35392
	ds_write_b16_d16_hi v154, v70 offset:35536
	ds_write_b16 v154, v71 offset:35680
	ds_write_b16_d16_hi v154, v71 offset:35824
	ds_write_b128 v156, v[72:75]
	ds_write_b128 v156, v[76:79] offset:17408
	ds_write_b16 v157, v76 offset:34816
	ds_write_b16_d16_hi v158, v76 offset:34960
	ds_write_b16 v157, v77 offset:35104
	ds_write_b16_d16_hi v157, v77 offset:35248
	ds_write_b16 v157, v78 offset:35392
	ds_write_b16_d16_hi v157, v78 offset:35536
	ds_write_b16 v157, v79 offset:35680
	ds_write_b16_d16_hi v157, v79 offset:35824
	ds_write_b16 v159, v80 offset:53248
	ds_write_b16_d16_hi v160, v80 offset:53392
	ds_write_b16 v159, v81 offset:53536
	ds_write_b16_d16_hi v159, v81 offset:53680
	ds_write_b16 v159, v82 offset:53824
	ds_write_b16_d16_hi v159, v82 offset:53968
	ds_write_b16 v159, v83 offset:54112
	ds_write_b16_d16_hi v159, v83 offset:54256
	s_waitcnt lgkmcnt(0)
	s_barrier
	s_setprio 0
	s_and_saveexec_b64 s[12:13], s[80:81]
	s_cbranch_execz .LBB0_1638
	v_add_u32_e32 v8, s92, v203
	v_ashrrev_i32_e32 v9, 31, v8
	v_lshlrev_b64 v[14:15], 11, v[8:9]
	v_lshl_add_u64 v[14:15], v[138:139], 0, v[14:15]
	global_store_dwordx2 v[14:15], v[4:5], off
	global_store_dwordx2 v[14:15], v[6:7], off offset:32
	s_and_b64 exec, exec, s[44:45]
	s_cbranch_execz .LBB0_1638
	v_lshlrev_b64 v[4:5], 7, v[8:9]
	v_lshl_add_u64 v[4:5], s[6:7], 0, v[4:5]
	global_store_dword v[4:5], v10, off

; __device__ __forceinline__ int opaque_bid() { int t = blockIdx.x * 2 + half_id(); asm volatile("" : "+s"(t)); return t; }
; __device__ __forceinline__ int half_id() { return __builtin_amdgcn_readfirstlane((int)(threadIdx.x >> 8)); }
; __global__ void __launch_bounds__(512, 2) fwd_megakernel(Params p) {
;     ...
;         for (int rep = 0; rep < REP_E2; ++rep)
; #pragma unroll 1
;         for (int u = opaque_bid(); u < 512; u += NVB) {
;           if (u & 1) { const WS ws = make_ws(p); rglru_unit(p, ws, j, u >> 1, rep < REP_E2 - 1); }
;           else { const WS ws = make_ws(p); gla_unit(p, ws, u >> 1, rep < REP_E2 - 1); }
;         }
.LBB0_1669:
	v_readfirstlane_b32 s4, v175
	s_nop 3
	s_lshr_b32 s4, s4, 8
	s_cmp_eq_u32 s4, 0
	s_cbranch_scc1 .Lrp0
	s_setprio 1
	s_branch .Lrp1
